# issue-slot trims: GEMM1 epilogue store s_nop removed (rotating quads), summary tile: last v_max sites folded, prefetch clause breaks by VALU
# speedup vs baseline: 1.0049x; 1.0017x over previous
.LBB0_292:
	v_lshl_or_b32 v140, s78, 8, v143
	v_ashrrev_i32_e32 v141, 31, v140
	v_lshl_add_u32 v145, s79, 8, v129
	v_lshl_add_u64 v[140:141], v[140:141], 1, s[36:37]
	v_cvt_pk_bf16_f32 v156, v124, v125
	v_cvt_pk_bf16_f32 v157, v126, v127
	v_mad_i64_i32 v[146:147], s[58:59], v145, s3, v[140:141]
	v_cvt_pk_bf16_f32 v158, v120, v121
	v_cvt_pk_bf16_f32 v159, v122, v123
	global_store_dwordx4 v[146:147], v[156:159], off sc1
	v_cvt_pk_bf16_f32 v160, v116, v117
	v_cvt_pk_bf16_f32 v161, v118, v119
	v_cvt_pk_bf16_f32 v162, v108, v109
	v_cvt_pk_bf16_f32 v163, v110, v111
	v_lshl_add_u64 v[116:117], v[146:147], 0, s[10:11]
	global_store_dwordx4 v[116:117], v[160:163], off sc1
	v_or_b32_e32 v108, 16, v145
	v_cvt_pk_bf16_f32 v164, v112, v113
	v_cvt_pk_bf16_f32 v165, v114, v115
	v_mad_i64_i32 v[108:109], s[58:59], v108, s3, v[140:141]
	v_cvt_pk_bf16_f32 v166, v104, v105
	v_cvt_pk_bf16_f32 v167, v106, v107
	global_store_dwordx4 v[108:109], v[164:167], off sc1
	v_cvt_pk_bf16_f32 v168, v100, v101
	v_cvt_pk_bf16_f32 v169, v102, v103
	v_cvt_pk_bf16_f32 v170, v92, v93
	v_cvt_pk_bf16_f32 v171, v94, v95
	v_lshl_add_u64 v[100:101], v[108:109], 0, s[10:11]
	global_store_dwordx4 v[100:101], v[168:171], off sc1
	v_or_b32_e32 v92, 32, v145
	v_cvt_pk_bf16_f32 v172, v96, v97
	v_cvt_pk_bf16_f32 v173, v98, v99
	v_mad_i64_i32 v[92:93], s[58:59], v92, s3, v[140:141]
	v_cvt_pk_bf16_f32 v174, v88, v89
	v_cvt_pk_bf16_f32 v175, v90, v91
	global_store_dwordx4 v[92:93], v[172:175], off sc1
	v_cvt_pk_bf16_f32 v176, v84, v85
	v_cvt_pk_bf16_f32 v177, v86, v87
	v_cvt_pk_bf16_f32 v178, v76, v77
	v_cvt_pk_bf16_f32 v179, v78, v79
	v_lshl_add_u64 v[84:85], v[92:93], 0, s[10:11]
	global_store_dwordx4 v[84:85], v[176:179], off sc1
	v_or_b32_e32 v76, 48, v145
	v_cvt_pk_bf16_f32 v180, v80, v81
	v_cvt_pk_bf16_f32 v181, v82, v83
	v_mad_i64_i32 v[76:77], s[58:59], v76, s3, v[140:141]
	v_cvt_pk_bf16_f32 v182, v72, v73
	v_cvt_pk_bf16_f32 v183, v74, v75
	global_store_dwordx4 v[76:77], v[180:183], off sc1
	v_cvt_pk_bf16_f32 v184, v68, v69
	v_cvt_pk_bf16_f32 v185, v70, v71
	v_cvt_pk_bf16_f32 v186, v64, v65
	v_cvt_pk_bf16_f32 v187, v66, v67
	v_lshl_add_u64 v[68:69], v[76:77], 0, s[10:11]
	global_store_dwordx4 v[68:69], v[184:187], off sc1
	v_add_u32_e32 v64, 0x80, v145
	v_cvt_pk_bf16_f32 v156, v60, v61
	v_cvt_pk_bf16_f32 v157, v62, v63
	v_mad_i64_i32 v[64:65], s[58:59], v64, s3, v[140:141]
	v_cvt_pk_bf16_f32 v158, v56, v57
	v_cvt_pk_bf16_f32 v159, v58, v59
	global_store_dwordx4 v[64:65], v[156:159], off sc1
	v_cvt_pk_bf16_f32 v160, v52, v53
	v_cvt_pk_bf16_f32 v161, v54, v55
	v_cvt_pk_bf16_f32 v162, v44, v45
	v_cvt_pk_bf16_f32 v163, v46, v47
	v_lshl_add_u64 v[52:53], v[64:65], 0, s[10:11]
	global_store_dwordx4 v[52:53], v[160:163], off sc1
	v_add_u32_e32 v44, 0x90, v145
	v_cvt_pk_bf16_f32 v164, v48, v49
	v_cvt_pk_bf16_f32 v165, v50, v51
	v_mad_i64_i32 v[44:45], s[58:59], v44, s3, v[140:141]
	v_cvt_pk_bf16_f32 v166, v40, v41
	v_cvt_pk_bf16_f32 v167, v42, v43
	global_store_dwordx4 v[44:45], v[164:167], off sc1
	v_cvt_pk_bf16_f32 v168, v36, v37
	v_cvt_pk_bf16_f32 v169, v38, v39
	v_cvt_pk_bf16_f32 v170, v28, v29
	v_cvt_pk_bf16_f32 v171, v30, v31
	v_lshl_add_u64 v[36:37], v[44:45], 0, s[10:11]
	global_store_dwordx4 v[36:37], v[168:171], off sc1
	v_add_u32_e32 v28, 0xa0, v145
	v_cvt_pk_bf16_f32 v172, v32, v33
	v_cvt_pk_bf16_f32 v173, v34, v35
	v_mad_i64_i32 v[28:29], s[58:59], v28, s3, v[140:141]
	v_cvt_pk_bf16_f32 v174, v24, v25
	v_cvt_pk_bf16_f32 v175, v26, v27
	global_store_dwordx4 v[28:29], v[172:175], off sc1
	v_cvt_pk_bf16_f32 v176, v20, v21
	v_cvt_pk_bf16_f32 v177, v22, v23
	v_cvt_pk_bf16_f32 v178, v12, v13
	v_cvt_pk_bf16_f32 v179, v14, v15
	v_lshl_add_u64 v[20:21], v[28:29], 0, s[10:11]
	global_store_dwordx4 v[20:21], v[176:179], off sc1
	v_add_u32_e32 v12, 0xb0, v145
	v_cvt_pk_bf16_f32 v180, v16, v17
	v_cvt_pk_bf16_f32 v181, v18, v19
	v_mad_i64_i32 v[12:13], s[58:59], v12, s3, v[140:141]
	v_cvt_pk_bf16_f32 v182, v8, v9
	v_cvt_pk_bf16_f32 v183, v10, v11
	global_store_dwordx4 v[12:13], v[180:183], off sc1
	v_cvt_pk_bf16_f32 v184, v4, v5
	v_lshl_add_u64 v[4:5], v[12:13], 0, s[10:11]
	v_cvt_pk_bf16_f32 v185, v6, v7
	v_cvt_pk_bf16_f32 v186, v0, v1
	v_cvt_pk_bf16_f32 v187, v2, v3
	s_andn2_b64 vcc, exec, s[40:41]
	global_store_dwordx4 v[4:5], v[184:187], off sc1
	s_mov_b64 s[40:41], -1
	s_cbranch_vccnz .LBB0_285
	s_andn2_b64 vcc, exec, s[34:35]
	s_cbranch_vccnz .LBB0_284
	s_branch .LBB0_284

.LBB0_428:
	v_mov_b32_e32 v105, v104
	v_mov_b32_e32 v106, v104
	v_mov_b32_e32 v107, v104
	v_mov_b32_e32 v97, v96
	v_mov_b32_e32 v98, v96
	s_waitcnt lgkmcnt(7)
	v_mfma_f32_16x16x32_bf16 v[114:117], v[24:27], v[56:59], v[104:107]
	v_mov_b32_e32 v99, v96
	v_add_u32_e32 v18, s34, v186
	v_lshl_add_u32 v5, v18, 1, v189
	v_mfma_f32_16x16x32_bf16 v[118:121], v[24:27], v[60:63], v[96:99]
	s_waitcnt lgkmcnt(6)
	v_mfma_f32_16x16x32_bf16 v[128:131], v[28:31], v[64:67], v[114:117]
	s_waitcnt lgkmcnt(5)
	v_mfma_f32_16x16x32_bf16 v[114:117], v[32:35], v[56:59], v[104:107]
	v_mfma_f32_16x16x32_bf16 v[204:207], v[28:31], v[68:71], v[118:121]
	s_waitcnt lgkmcnt(4)
	v_mfma_f32_16x16x32_bf16 v[218:221], v[36:39], v[64:67], v[114:117]
	ds_read_u16 v7, v5
	ds_read_u16 v17, v5 offset:1040
	ds_read_u16 v19, v5 offset:2080
	s_nop 1
	ds_read_u16 v114, v5 offset:3120
	ds_read_u16 v115, v5 offset:4160
	ds_read_u16 v125, v5 offset:5200
	ds_read_u16 v154, v5 offset:6240
	ds_read_u16 v155, v5 offset:7280
	s_waitcnt lgkmcnt(4)
	v_lshlrev_b32_e32 v123, 16, v114
	s_waitcnt lgkmcnt(3)
	v_lshlrev_b32_e32 v124, 16, v115
	v_mfma_f32_16x16x32_bf16 v[118:121], v[32:35], v[60:63], v[96:99]
	v_lshlrev_b32_e32 v126, 16, v7
	v_lshlrev_b32_e32 v127, 16, v17
	v_lshlrev_b32_e32 v122, 16, v19
	v_mfma_f32_16x16x32_bf16 v[114:117], v[40:43], v[56:59], v[104:107]
	s_waitcnt lgkmcnt(2)
	v_lshlrev_b32_e32 v125, 16, v125
	v_mfma_f32_16x16x32_bf16 v[226:229], v[40:43], v[60:63], v[96:99]
	v_mfma_f32_16x16x32_bf16 v[106:109], v[48:51], v[56:59], v[104:107]
	v_exp_f32_e32 v110, v128
	v_exp_f32_e32 v111, v129
	v_mfma_f32_16x16x32_bf16 v[96:99], v[48:51], v[60:63], v[96:99]
	v_exp_f32_e32 v102, v204
	v_exp_f32_e32 v103, v205
	v_pk_add_f32 v[100:101], v[110:111], 1.0 op_sel_hi:[1,0]
	v_mfma_f32_16x16x32_bf16 v[222:225], v[36:39], v[68:71], v[118:121]
	v_rcp_f32_e32 v100, v100
	v_rcp_f32_e32 v101, v101
	v_mfma_f32_16x16x32_bf16 v[226:229], v[44:47], v[68:71], v[226:229]
	s_waitcnt lgkmcnt(1)
	v_lshlrev_b32_e32 v120, 16, v154
	s_waitcnt lgkmcnt(0)
	v_lshlrev_b32_e32 v121, 16, v155
	ds_read_u16 v7, v5 offset:8320
	ds_read_u16 v17, v5 offset:9360
	ds_read_u16 v19, v5 offset:10400
	ds_read_u16 v154, v5 offset:11440
	ds_read_u16 v155, v5 offset:12480
	ds_read_u16 v203, v5 offset:13520
	ds_read_u16 v208, v5 offset:14560
	ds_read_u16 v5, v5 offset:15600
	v_mfma_f32_16x16x32_bf16 v[88:91], v[52:55], v[68:71], v[96:99]
	v_exp_f32_e32 v209, v229
	s_waitcnt lgkmcnt(7)
	v_lshlrev_b32_e32 v118, 16, v7
	s_waitcnt lgkmcnt(1)
	v_lshlrev_b32_e32 v104, 16, v208
	v_pk_add_f32 v[98:99], v[102:103], 1.0 op_sel_hi:[1,0]
	v_exp_f32_e32 v102, v130
	v_exp_f32_e32 v103, v131
	v_pk_mul_f32 v[96:97], v[100:101], v[6:7] op_sel_hi:[1,0]
	v_mfma_f32_16x16x32_bf16 v[230:233], v[44:47], v[64:67], v[114:117]
	v_exp_f32_e32 v96, v96
	v_pk_add_f32 v[102:103], v[102:103], 1.0 op_sel_hi:[1,0]
	v_exp_f32_e32 v97, v97
	v_rcp_f32_e32 v102, v102
	v_rcp_f32_e32 v103, v103
	s_waitcnt lgkmcnt(0)
	v_lshlrev_b32_e32 v105, 16, v5
	v_pk_fma_f32 v[100:101], v[96:97], v[96:97], 1.0 op_sel_hi:[1,1,0] neg_lo:[1,0,0] neg_hi:[1,0,0] clamp
	v_mfma_f32_16x16x32_bf16 v[92:95], v[52:55], v[64:67], v[106:109]
	v_mul_f32_e64 v102, v102, v6
	v_mul_f32_e64 v103, v103, v6
	v_exp_f32_e32 v110, v102
	v_exp_f32_e32 v111, v103
	v_exp_f32_e32 v102, v218
	s_cmpk_eq_i32 s30, 0x1800
	s_cbranch_scc1 .Lsl_skip1
	v_lshl_add_u64 v[64:65], v[242:243], 0, s[30:31]
	v_lshl_add_u64 v[68:69], v[244:245], 0, s[30:31]
	v_add_u32_e32 v197, s39, v193
	v_add_u32_e32 v199, s39, v194
	global_load_dwordx4 v[56:59], v[64:65], off offset:2048
	global_load_dwordx4 v[60:63], v[68:69], off offset:2048
	v_lshlrev_b32_e32 v197, 2, v197
	global_load_dwordx4 v[64:67], v[64:65], off offset:2112
	global_load_dwordx4 v[68:71], v[68:69], off offset:2112
	global_load_dword v198, v197, s[22:23] offset:2112
	v_lshlrev_b32_e32 v199, 2, v199
	global_load_dword v197, v197, s[22:23] offset:64
	global_load_dword v199, v199, s[6:7] offset:64

.LBB0_430:
	s_or_b64 exec, exec, s[34:35]
	s_waitcnt lgkmcnt(4)
	v_mov_b32_e32 v17, v16
	v_mov_b32_e32 v18, v16
	v_mov_b32_e32 v19, v16
	v_mov_b32_e32 v5, v4
	v_mov_b32_e32 v6, v4
	v_mfma_f32_16x16x32_bf16 v[220:223], v[24:27], v[72:75], v[16:19]
	s_waitcnt lgkmcnt(0)
	v_mov_b32_e32 v7, v4
	v_mfma_f32_16x16x32_bf16 v[220:223], v[28:31], v[76:79], v[220:223]
	s_nop 0
	v_mfma_f32_16x16x32_bf16 v[224:227], v[24:27], v[80:83], v[4:7]
	v_mfma_f32_16x16x32_bf16 v[224:227], v[28:31], v[84:87], v[224:227]
	s_nop 4
	v_exp_f32_e32 v110, v220
	v_exp_f32_e32 v111, v221
	v_mfma_f32_16x16x32_bf16 v[228:231], v[32:35], v[72:75], v[16:19]
	v_add_f32_e64 v110, v110, 1.0
	v_add_f32_e64 v111, v111, 1.0
	v_exp_f32_e32 v130, v224
	v_exp_f32_e32 v131, v225
	v_rcp_f32_e32 v110, v110
	v_rcp_f32_e32 v111, v111
	v_mfma_f32_16x16x32_bf16 v[228:231], v[36:39], v[76:79], v[228:231]
	v_add_f32_e64 v130, v130, 1.0
	v_add_f32_e64 v131, v131, 1.0
	v_exp_f32_e32 v224, v222
	v_pk_mul_f32 v[110:111], v[110:111], v[148:149] op_sel_hi:[1,0]
	v_rcp_f32_e32 v220, v130
	v_rcp_f32_e32 v221, v131
	v_exp_f32_e32 v130, v110
	v_exp_f32_e32 v131, v111
	v_exp_f32_e32 v225, v223
	v_pk_mul_f32 v[110:111], v[220:221], v[126:127]
	v_mfma_f32_16x16x32_bf16 v[220:223], v[40:43], v[72:75], v[16:19]
	v_fma_f32 v126, -v130, v130, 1.0 clamp
	v_fma_f32 v127, -v131, v131, 1.0 clamp
	v_pk_add_f32 v[224:225], v[224:225], 1.0 op_sel_hi:[1,0]
	v_sqrt_f32_e32 v126, v126
	v_mfma_f32_16x16x32_bf16 v[16:19], v[48:51], v[72:75], v[16:19]
	v_exp_f32_e32 v22, v228
	v_exp_f32_e32 v23, v229
	v_sqrt_f32_e32 v127, v127
	v_mfma_f32_16x16x32_bf16 v[232:235], v[32:35], v[80:83], v[4:7]
	v_exp_f32_e32 v226, v226
	v_exp_f32_e32 v227, v227
	v_rcp_f32_e32 v224, v224
	v_mfma_f32_16x16x32_bf16 v[236:239], v[40:43], v[80:83], v[4:7]
	v_rcp_f32_e32 v225, v225
	v_pk_mul_f32 v[110:111], v[110:111], v[126:127]
	v_pk_add_f32 v[240:241], v[226:227], 1.0 op_sel_hi:[1,0]
	v_mfma_f32_16x16x32_bf16 v[4:7], v[48:51], v[80:83], v[4:7]
	v_mul_f32_e64 v126, v224, v148
	v_mul_f32_e64 v127, v225, v148
	v_exp_f32_e32 v126, v126
	v_mfma_f32_16x16x32_bf16 v[220:223], v[44:47], v[76:79], v[220:223]
	v_exp_f32_e32 v127, v127
	s_nop 0
	v_pk_fma_f32 v[20:21], v[126:127], v[126:127], 1.0 op_sel_hi:[1,1,0] neg_lo:[1,0,0] neg_hi:[1,0,0] clamp
	v_mfma_f32_16x16x32_bf16 v[10:13], v[52:55], v[76:79], v[16:19]
	v_sqrt_f32_e32 v8, v20
	s_nop 0
	v_pk_add_f32 v[18:19], v[22:23], 1.0 op_sel_hi:[1,0]
	v_mfma_f32_16x16x32_bf16 v[232:235], v[36:39], v[84:87], v[232:235]
	s_nop 2
	v_exp_f32_e32 v10, v10
	v_exp_f32_e32 v11, v11
	v_exp_f32_e32 v12, v12
	v_mfma_f32_16x16x32_bf16 v[224:227], v[44:47], v[84:87], v[236:239]
	v_exp_f32_e32 v13, v13
	v_exp_f32_e32 v22, v232
	v_exp_f32_e32 v23, v233
	v_mfma_f32_16x16x32_bf16 v[14:17], v[52:55], v[84:87], v[4:7]
	v_rcp_f32_e32 v0, v18
	v_rcp_f32_e32 v1, v19
	v_rcp_f32_e32 v236, v240
	v_rcp_f32_e32 v237, v241
	s_cmpk_eq_i32 s30, 0x1800
	s_cbranch_scc1 .Lsl_skip2
	v_lshl_add_u64 v[76:77], v[246:247], 0, s[30:31]
	v_lshl_add_u64 v[84:85], v[248:249], 0, s[30:31]
	v_add_u32_e32 v200, s39, v193
	v_add_u32_e32 v202, s39, v194
	global_load_dwordx4 v[72:75], v[76:77], off offset:2048
	global_load_dwordx4 v[80:83], v[84:85], off offset:2048
	v_lshlrev_b32_e32 v200, 2, v200
	global_load_dwordx4 v[76:79], v[76:77], off offset:2112
	v_add_u32_e32 v200, 0x1000, v200
	global_load_dwordx4 v[84:87], v[84:85], off offset:2112
	global_load_dword v201, v200, s[22:23] offset:2112
	v_lshlrev_b32_e32 v202, 2, v202
	global_load_dword v200, v200, s[22:23] offset:64
	global_load_dword v202, v202, s[6:7] offset:2112
